# row phases: non-temporal hint on the read-once bf16 row loads (x, y, y2)
# baseline (speedup 1.0000x reference)
.LBB0_115:
	v_lshl_add_u64 v[62:63], v[48:49], 0, v[36:37]
	v_lshl_add_u64 v[60:61], v[52:53], 0, v[36:37]
	global_load_dwordx2 v[8:9], v[62:63], off offset:2048 nt
	global_load_dwordx2 v[4:5], v[62:63], off offset:2560 nt
	global_load_dwordx2 v[0:1], v[62:63], off offset:3072 nt
	global_load_dwordx2 v[68:69], v[62:63], off offset:3584 nt
	global_load_dwordx2 v[10:11], v[60:61], off offset:2048 nt
	global_load_dwordx2 v[6:7], v[60:61], off offset:2560 nt
	global_load_dwordx2 v[2:3], v[60:61], off offset:3072 nt
	global_load_dwordx2 v[66:67], v[60:61], off offset:3584 nt
	v_lshl_add_u64 v[58:59], v[46:47], 0, v[36:37]
	v_add_co_u32_e32 v12, vcc, 0xa280000, v58
	v_lshl_add_u64 v[56:57], v[50:51], 0, v[36:37]
	s_nop 0
	v_addc_co_u32_e32 v13, vcc, 0, v59, vcc
	global_load_dwordx2 v[112:113], v[12:13], off nt
	v_add_co_u32_e32 v12, vcc, 0xa280000, v56
	v_add_u32_e32 v152, 0x8000, v130
	s_nop 0
	v_addc_co_u32_e32 v13, vcc, 0, v57, vcc
	global_load_dwordx2 v[96:97], v[12:13], off nt
	v_lshlrev_b64 v[12:13], 11, v[130:131]
	v_cmp_lt_i32_e64 s[4:5], s3, v152
	v_lshl_add_u64 v[12:13], v[38:39], 0, v[12:13]
	v_mov_b32_e32 v98, 0
	v_mov_b32_e32 v120, 0
	v_mov_b32_e32 v121, 0
	s_and_saveexec_b64 s[6:7], s[4:5]
	s_cbranch_execz .LBB0_117
	global_load_dwordx2 v[120:121], v[12:13], off nt
.LBB0_117:
	s_or_b64 exec, exec, s[6:7]
	v_add_u32_e32 v14, 0x800, v130
	v_mov_b32_e32 v15, v131
	s_movk_i32 s0, 0x77ff
	v_lshlrev_b64 v[14:15], 11, v[14:15]
	v_cmp_lt_i32_e64 s[6:7], s0, v152
	v_lshl_add_u64 v[14:15], v[38:39], 0, v[14:15]
	v_mov_b32_e32 v99, 0
	s_and_saveexec_b64 s[16:17], s[6:7]
	s_cbranch_execz .LBB0_119
	global_load_dwordx2 v[98:99], v[14:15], off nt

.LBB0_374:
	v_lshl_add_u64 v[62:63], v[48:49], 0, v[36:37]
	v_lshl_add_u64 v[60:61], v[52:53], 0, v[36:37]
	global_load_dwordx2 v[8:9], v[62:63], off offset:2048 nt
	global_load_dwordx2 v[4:5], v[62:63], off offset:2560 nt
	global_load_dwordx2 v[0:1], v[62:63], off offset:3072 nt
	global_load_dwordx2 v[68:69], v[62:63], off offset:3584 nt
	global_load_dwordx2 v[10:11], v[60:61], off offset:2048 nt
	global_load_dwordx2 v[6:7], v[60:61], off offset:2560 nt
	global_load_dwordx2 v[2:3], v[60:61], off offset:3072 nt
	global_load_dwordx2 v[66:67], v[60:61], off offset:3584 nt
	v_lshl_add_u64 v[58:59], v[46:47], 0, v[36:37]
	v_add_co_u32_e32 v12, vcc, 0xa280000, v58
	v_lshl_add_u64 v[56:57], v[50:51], 0, v[36:37]
	s_nop 0
	v_addc_co_u32_e32 v13, vcc, 0, v59, vcc
	global_load_dwordx2 v[112:113], v[12:13], off nt
	v_add_co_u32_e32 v12, vcc, 0xa280000, v56
	v_add_u32_e32 v152, 0x8000, v130
	s_nop 0
	v_addc_co_u32_e32 v13, vcc, 0, v57, vcc
	global_load_dwordx2 v[96:97], v[12:13], off nt
	s_movk_i32 s0, 0x7fff
	v_lshlrev_b64 v[12:13], 11, v[130:131]
	v_cmp_lt_i32_e64 s[4:5], s0, v152
	v_lshl_add_u64 v[12:13], v[38:39], 0, v[12:13]
	v_mov_b32_e32 v98, 0
	v_mov_b32_e32 v120, 0
	v_mov_b32_e32 v121, 0
	s_and_saveexec_b64 s[6:7], s[4:5]
	s_cbranch_execz .LBB0_376
	global_load_dwordx2 v[120:121], v[12:13], off nt
.LBB0_376:
	s_or_b64 exec, exec, s[6:7]
	v_add_u32_e32 v14, 0x800, v130
	v_mov_b32_e32 v15, v131
	s_movk_i32 s0, 0x77ff
	v_lshlrev_b64 v[14:15], 11, v[14:15]
	v_cmp_lt_i32_e64 s[6:7], s0, v152
	v_lshl_add_u64 v[14:15], v[38:39], 0, v[14:15]
	v_mov_b32_e32 v99, 0
	s_and_saveexec_b64 s[18:19], s[6:7]
	s_cbranch_execz .LBB0_378
	global_load_dwordx2 v[98:99], v[14:15], off nt
.LBB0_378:
	s_or_b64 exec, exec, s[18:19]
	v_add_co_u32_e32 v16, vcc, 0xa280000, v58
	v_mov_b32_e32 v104, 0
	s_nop 0
	v_addc_co_u32_e32 v17, vcc, 0, v59, vcc
	global_load_dwordx2 v[116:117], v[16:17], off offset:512 nt
	v_add_co_u32_e32 v16, vcc, 0xa280000, v56
	v_mov_b32_e32 v124, 0
	s_nop 0
	v_addc_co_u32_e32 v17, vcc, 0, v57, vcc
	global_load_dwordx2 v[108:109], v[16:17], off offset:512
	v_mov_b32_e32 v125, 0
	s_and_saveexec_b64 s[18:19], s[4:5]
	s_cbranch_execz .LBB0_380
	global_load_dwordx2 v[124:125], v[12:13], off offset:512

.LBB0_430:
	s_andn2_saveexec_b64 s[4:5], s[4:5]
	v_lshl_add_u64 v[104:105], v[100:101], 0, s[28:29]
	v_mov_b64_e32 v[0:1], v[102:103]
	s_or_b64 exec, exec, s[4:5]
	v_readlane_b32 s36, v253, 28
	s_movk_i32 s0, 0x2000
	v_readlane_b32 s37, v253, 29
	v_readlane_b32 s39, v253, 31
	v_add_u32_e32 v40, 0xffffe000, v34
	v_lshl_add_u64 v[2:3], v[94:95], 0, s[28:29]
	v_cmp_gt_i32_e64 s[4:5], s0, v34
	v_readlane_b32 s38, v253, 30
	v_mov_b32_e32 v4, s39
	v_mov_b32_e32 v5, s37
	v_cndmask_b32_e64 v3, 0, v3, s[4:5]
	v_cndmask_b32_e64 v2, v40, v2, s[4:5]
	v_cndmask_b32_e64 v5, v4, v5, s[4:5]
	v_mov_b32_e32 v4, s38
	v_mov_b32_e32 v6, s36
	v_cndmask_b32_e64 v4, v4, v6, s[4:5]
	v_lshlrev_b64 v[2:3], 12, v[2:3]
	v_lshl_add_u64 v[2:3], v[4:5], 0, v[2:3]
	v_lshlrev_b32_e32 v130, 2, v78
	v_lshl_add_u64 v[2:3], v[2:3], 0, v[130:131]
	v_lshl_add_u64 v[0:1], v[0:1], 0, v[130:131]
	global_load_dwordx4 v[28:31], v[2:3], off
	global_load_dwordx4 v[20:23], v[2:3], off offset:1024
	global_load_dwordx4 v[24:27], v[0:1], off
	global_load_dwordx4 v[16:19], v[0:1], off offset:1024
	global_load_dwordx4 v[12:15], v[2:3], off offset:2048
	global_load_dwordx4 v[4:7], v[2:3], off offset:3072
	global_load_dwordx4 v[8:11], v[0:1], off offset:2048
	s_nop 0
	global_load_dwordx4 v[0:3], v[0:1], off offset:3072
	v_lshl_add_u64 v[106:107], v[96:97], 0, v[80:81]
	v_add_co_u32_e32 v36, vcc, 0xa280000, v106
	v_lshlrev_b64 v[108:109], 11, v[104:105]
	s_nop 0
	v_addc_co_u32_e32 v37, vcc, 0, v107, vcc
	v_lshl_add_u64 v[32:33], v[82:83], 0, v[108:109]
	global_load_dwordx2 v[146:147], v[36:37], off nt
	global_load_dwordx2 v[116:117], v[32:33], off nt
	v_add_u32_e32 v36, 0xffff8000, v34
	v_mov_b32_e32 v37, v131
	s_movk_i32 s0, 0x7fff
	v_lshlrev_b64 v[36:37], 11, v[36:37]
	v_cmp_lt_i32_e64 s[6:7], s0, v34
	v_lshl_add_u64 v[36:37], v[84:85], 0, v[36:37]
	v_mov_b32_e32 v120, 0
	v_mov_b32_e32 v154, 0
	v_mov_b32_e32 v155, 0
	v_readlane_b32 s40, v253, 32
	v_readlane_b32 s41, v253, 33
	v_readlane_b32 s42, v253, 34
	v_readlane_b32 s43, v253, 35
	s_and_saveexec_b64 s[8:9], s[6:7]
	s_cbranch_execz .LBB0_434
	global_load_dwordx2 v[154:155], v[36:37], off nt
.LBB0_434:
	s_or_b64 exec, exec, s[8:9]
	s_movk_i32 s0, 0x77ff
	v_cmp_lt_i32_e64 s[8:9], s0, v34
	v_add_u32_e32 v34, 0xffff8800, v34
	v_mov_b32_e32 v35, v131
	v_lshlrev_b64 v[34:35], 11, v[34:35]
	v_lshl_add_u64 v[38:39], v[84:85], 0, v[34:35]
	v_mov_b32_e32 v121, 0
	s_and_saveexec_b64 s[18:19], s[8:9]
	s_cbranch_execz .LBB0_436
	global_load_dwordx2 v[120:121], v[38:39], off nt
.LBB0_436:
	s_or_b64 exec, exec, s[18:19]
	v_add_co_u32_e32 v34, vcc, 0xa280000, v106
	v_mov_b32_e32 v118, 0
	s_nop 0
	v_addc_co_u32_e32 v35, vcc, 0, v107, vcc
	global_load_dwordx2 v[150:151], v[34:35], off offset:512 nt
	global_load_dwordx2 v[122:123], v[32:33], off offset:512 nt
	v_mov_b32_e32 v152, 0
	v_mov_b32_e32 v153, 0
	s_and_saveexec_b64 s[18:19], s[6:7]
	s_cbranch_execz .LBB0_438
	global_load_dwordx2 v[152:153], v[36:37], off offset:512 nt
.LBB0_438:
	s_or_b64 exec, exec, s[18:19]
	v_mov_b32_e32 v119, 0
	s_and_saveexec_b64 s[18:19], s[8:9]
	s_cbranch_execz .LBB0_440
	global_load_dwordx2 v[118:119], v[38:39], off offset:512 nt

.LBB0_1360:
	v_lshl_add_u64 v[62:63], v[48:49], 0, v[36:37]
	v_lshl_add_u64 v[60:61], v[52:53], 0, v[36:37]
	global_load_dwordx2 v[8:9], v[62:63], off offset:2048 nt
	global_load_dwordx2 v[4:5], v[62:63], off offset:2560 nt
	global_load_dwordx2 v[0:1], v[62:63], off offset:3072 nt
	global_load_dwordx2 v[68:69], v[62:63], off offset:3584 nt
	global_load_dwordx2 v[10:11], v[60:61], off offset:2048 nt
	global_load_dwordx2 v[6:7], v[60:61], off offset:2560 nt
	global_load_dwordx2 v[2:3], v[60:61], off offset:3072 nt
	global_load_dwordx2 v[66:67], v[60:61], off offset:3584 nt
	v_lshl_add_u64 v[58:59], v[46:47], 0, v[36:37]
	v_add_co_u32_e32 v12, vcc, 0xa280000, v58
	v_lshl_add_u64 v[56:57], v[50:51], 0, v[36:37]
	s_nop 0
	v_addc_co_u32_e32 v13, vcc, 0, v59, vcc
	global_load_dwordx2 v[110:111], v[12:13], off nt
	v_add_co_u32_e32 v12, vcc, 0xa280000, v56
	v_add_u32_e32 v150, 0x8000, v130
	s_nop 0
	v_addc_co_u32_e32 v13, vcc, 0, v57, vcc
	global_load_dwordx2 v[94:95], v[12:13], off nt
	s_movk_i32 s0, 0x7fff
	v_lshlrev_b64 v[12:13], 11, v[130:131]
	v_cmp_lt_i32_e64 s[4:5], s0, v150
	v_lshl_add_u64 v[12:13], v[38:39], 0, v[12:13]
	v_mov_b32_e32 v96, 0
	v_mov_b32_e32 v118, 0
	v_mov_b32_e32 v119, 0
	s_and_saveexec_b64 s[6:7], s[4:5]
	s_cbranch_execz .LBB0_1362
	global_load_dwordx2 v[118:119], v[12:13], off nt

.LBB0_1597:
	v_lshl_add_u64 v[8:9], v[40:41], 0, v[30:31]
	v_lshl_add_u64 v[10:11], v[42:43], 0, v[30:31]
	global_load_dwordx2 v[4:5], v[8:9], off offset:2048 nt
	global_load_dwordx2 v[0:1], v[8:9], off offset:2560 nt
	global_load_dwordx2 v[56:57], v[8:9], off offset:3072 nt
	global_load_dwordx2 v[52:53], v[8:9], off offset:3584 nt
	global_load_dwordx2 v[6:7], v[10:11], off offset:2048 nt
	global_load_dwordx2 v[2:3], v[10:11], off offset:2560 nt
	global_load_dwordx2 v[54:55], v[10:11], off offset:3072 nt
	global_load_dwordx2 v[50:51], v[10:11], off offset:3584 nt
	v_lshl_add_u64 v[10:11], v[38:39], 0, v[30:31]
	v_add_co_u32_e32 v12, vcc, 0xa280000, v10
	v_lshl_add_u64 v[8:9], v[44:45], 0, v[30:31]
	s_nop 0
	v_addc_co_u32_e32 v13, vcc, 0, v11, vcc
	global_load_dwordx2 v[84:85], v[12:13], off nt
	v_add_co_u32_e32 v12, vcc, 0xa280000, v8
	v_add_u32_e32 v113, 0x8000, v28
	s_nop 0
	v_addc_co_u32_e32 v13, vcc, 0, v9, vcc
	global_load_dwordx2 v[90:91], v[12:13], off nt
	v_lshlrev_b64 v[12:13], 11, v[28:29]
	v_cmp_lt_i32_e64 s[0:1], s18, v113
	v_lshl_add_u64 v[12:13], v[32:33], 0, v[12:13]
	v_mov_b32_e32 v86, 0
	v_mov_b32_e32 v87, 0
	s_and_saveexec_b64 s[2:3], s[0:1]
	s_cbranch_execz .LBB0_1599
	global_load_dwordx2 v[86:87], v[12:13], off nt
.LBB0_1599:
	s_or_b64 exec, exec, s[2:3]
	v_add_u32_e32 v14, 0x800, v28
	v_mov_b32_e32 v15, v29
	v_lshlrev_b64 v[14:15], 11, v[14:15]
	v_cmp_lt_i32_e64 s[2:3], s19, v113
	v_lshl_add_u64 v[14:15], v[32:33], 0, v[14:15]
	v_mov_b32_e32 v88, 0
	v_mov_b32_e32 v104, 0
	v_mov_b32_e32 v105, 0
	s_and_saveexec_b64 s[16:17], s[2:3]
	s_cbranch_execz .LBB0_1601
	global_load_dwordx2 v[104:105], v[14:15], off nt
.LBB0_1601:
	s_or_b64 exec, exec, s[16:17]
	v_add_co_u32_e32 v16, vcc, 0xa280000, v10
	v_mov_b32_e32 v89, 0
	s_nop 0
	v_addc_co_u32_e32 v17, vcc, 0, v11, vcc
	global_load_dwordx2 v[102:103], v[16:17], off offset:512 nt
	v_add_co_u32_e32 v16, vcc, 0xa280000, v8
	s_nop 1
	v_addc_co_u32_e32 v17, vcc, 0, v9, vcc
	global_load_dwordx2 v[94:95], v[16:17], off offset:512 nt
	s_and_saveexec_b64 s[16:17], s[0:1]
	s_cbranch_execz .LBB0_1603
	global_load_dwordx2 v[88:89], v[12:13], off offset:512 nt
.LBB0_1603:
	s_or_b64 exec, exec, s[16:17]
	v_mov_b32_e32 v78, 0
	v_mov_b32_e32 v106, 0
	v_mov_b32_e32 v107, 0
	s_and_saveexec_b64 s[16:17], s[2:3]
	s_cbranch_execz .LBB0_1605
	global_load_dwordx2 v[106:107], v[14:15], off offset:512 nt
.LBB0_1605:
	s_or_b64 exec, exec, s[16:17]
	v_add_co_u32_e32 v16, vcc, 0xa280000, v10
	v_mov_b32_e32 v79, 0
	s_nop 0
	v_addc_co_u32_e32 v17, vcc, 0, v11, vcc
	global_load_dwordx2 v[96:97], v[16:17], off offset:1024 nt
	v_add_co_u32_e32 v16, vcc, 0xa280000, v8
	s_nop 1
	v_addc_co_u32_e32 v17, vcc, 0, v9, vcc
	global_load_dwordx2 v[92:93], v[16:17], off offset:1024 nt
	s_and_saveexec_b64 s[16:17], s[0:1]
	s_cbranch_execz .LBB0_1607
	global_load_dwordx2 v[78:79], v[12:13], off offset:1024 nt
.LBB0_1607:
	s_or_b64 exec, exec, s[16:17]
	v_mov_b32_e32 v80, 0
	v_mov_b32_e32 v100, 0
	v_mov_b32_e32 v101, 0
	s_and_saveexec_b64 s[16:17], s[2:3]
	s_cbranch_execz .LBB0_1609
	global_load_dwordx2 v[100:101], v[14:15], off offset:1024 nt
.LBB0_1609:
	s_or_b64 exec, exec, s[16:17]
	v_add_co_u32_e32 v10, vcc, 0xa280000, v10
	v_mov_b32_e32 v81, 0
	s_nop 0
	v_addc_co_u32_e32 v11, vcc, 0, v11, vcc
	v_add_co_u32_e32 v8, vcc, 0xa280000, v8
	global_load_dwordx2 v[98:99], v[10:11], off offset:1536 nt
	s_nop 0
	v_addc_co_u32_e32 v9, vcc, 0, v9, vcc
	global_load_dwordx2 v[74:75], v[8:9], off offset:1536 nt
	s_and_saveexec_b64 s[16:17], s[0:1]
	s_cbranch_execz .LBB0_1611
	global_load_dwordx2 v[80:81], v[12:13], off offset:1536 nt
.LBB0_1611:
	s_or_b64 exec, exec, s[16:17]
	v_mov_b32_e32 v82, 0
	v_mov_b32_e32 v83, 0
	s_and_saveexec_b64 s[0:1], s[2:3]
	s_cbranch_execz .LBB0_1596
	global_load_dwordx2 v[82:83], v[14:15], off offset:1536 nt
	s_branch .LBB0_1596
